# v33 + in-proj epilogue de-serialised: second row-half sumsq load issued with the first (one vmcnt(0) instead of two)
# speedup vs baseline: 1.0045x; 1.0026x over previous
; __device__ __forceinline__ float row_rstd(const float* ss, int row) { return 1.0f / sqrtf(ss[row] * (1.0f / DM) + 1e-6f); }
;     __device__ __forceinline__ void operator()(const f32x4 (&acc)[2][2][4][2], const Unit& u, int wr, int wc, int fr, int fq) const {
;         const int row0 = u.pm * BM + wr * 64 + fr, col0 = u.pn * BM + wc * 64 + 8 * fq;
;         const bool lat = u.pm < ML / BM; const int s = lat ? (u.pm >> 5) : 4;
;         const float* bp = bias + (size_t)s * BIAS_N + col0;
;         const f32x4 b00 = *(const f32x4*)bp, b01 = *(const f32x4*)(bp + 4), b10 = *(const f32x4*)(bp + 32), b11 = *(const f32x4*)(bp + 36);
;         const int lane = fq * 16 + fr;
;         const float rsl0 = row_rstd(ss, u.pm * BM + wr * 64 + lane), rsl1 = row_rstd(ss, u.pm * BM + HALF + wr * 64 + lane);
;         const bool odd = (fr & 1) != 0;
;         const bool ktile = (u.pn == 2) || (u.pn == 3) || (u.pn == 12), wa = (u.pn == 12);
;         float part[2][4]; f32x4 g00, g01, g10, g11;
.LBB0_540:
	s_lshl_b32 s0, s2, 8
	s_add_i32 s0, s0, s62
	s_lshl_b64 s[2:3], s[16:17], 2
	v_lshl_or_b32 v182, s46, 8, v202
	s_add_u32 s2, s63, s2
	v_or_b32_e32 v98, s0, v187
	s_addc_u32 s3, s64, s3
	v_ashrrev_i32_e32 v183, 31, v182
	v_ashrrev_i32_e32 v99, 31, v98
	v_lshl_add_u64 v[38:39], v[182:183], 2, s[2:3]
	v_lshl_add_u64 v[98:99], v[98:99], 2, s[74:75]
	global_load_dwordx4 v[42:45], v[38:39], off offset:16
	global_load_dwordx4 v[46:49], v[38:39], off
	global_load_dwordx4 v[34:37], v[38:39], off offset:144
	s_nop 0
	global_load_dwordx4 v[38:41], v[38:39], off offset:128
	s_cmp_lt_u32 s46, 13
	global_load_dword v98, v[98:99], off
	v_add_u32_e32 v110, s0, v193
	v_ashrrev_i32_e32 v111, 31, v110
	v_lshl_add_u64 v[110:111], v[110:111], 2, s[74:75]
	global_load_dword v112, v[110:111], off
	s_waitcnt vmcnt(0)
	v_fmamk_f32 v98, v98, 0x3a000000, v206
	v_cmp_gt_f32_e32 vcc, s70, v98
	v_mul_f32_e32 v99, 0x4f800000, v98
	s_nop 0
	v_cndmask_b32_e32 v98, v98, v99, vcc
	v_sqrt_f32_e32 v99, v98
	s_nop 0
	v_add_u32_e32 v100, -1, v99
	v_fma_f32 v101, -v100, v99, v98
	v_cmp_ge_f32_e64 s[2:3], 0, v101
	v_add_u32_e32 v101, 1, v99
	s_nop 0
	v_cndmask_b32_e64 v100, v99, v100, s[2:3]
	v_fma_f32 v99, -v101, v99, v98
	v_cmp_lt_f32_e64 s[2:3], 0, v99
	s_nop 1
	v_cndmask_b32_e64 v99, v100, v101, s[2:3]
	v_mul_f32_e32 v100, 0x37800000, v99
	v_cndmask_b32_e32 v99, v99, v100, vcc
	v_cmp_class_f32_e32 vcc, v98, v207
	s_nop 1
	v_cndmask_b32_e32 v98, v99, v98, vcc
	v_div_scale_f32 v99, s[2:3], v98, v98, 1.0
	v_rcp_f32_e32 v100, v99
	s_nop 0
	v_fma_f32 v101, -v99, v100, 1.0
	v_fmac_f32_e32 v100, v101, v100
	v_div_scale_f32 v101, vcc, 1.0, v98, 1.0
	v_mul_f32_e32 v102, v101, v100
	v_fma_f32 v103, -v99, v102, v101
	v_fmac_f32_e32 v102, v103, v100
	v_fma_f32 v99, -v99, v102, v101
	v_div_fmas_f32 v99, v99, v100, v102
	v_div_fixup_f32 v216, v99, v98, 1.0
	v_fmamk_f32 v98, v112, 0x3a000000, v206
	v_cmp_gt_f32_e32 vcc, s70, v98
	v_mul_f32_e32 v99, 0x4f800000, v98
	s_nop 0
	v_cndmask_b32_e32 v98, v98, v99, vcc
	v_sqrt_f32_e32 v99, v98
	s_nop 0
	v_add_u32_e32 v100, -1, v99
	v_fma_f32 v101, -v100, v99, v98
	v_cmp_ge_f32_e64 s[2:3], 0, v101
	v_add_u32_e32 v101, 1, v99
	s_nop 0
	v_cndmask_b32_e64 v100, v99, v100, s[2:3]
	v_fma_f32 v99, -v101, v99, v98
	v_cmp_lt_f32_e64 s[2:3], 0, v99
	s_nop 1
	v_cndmask_b32_e64 v99, v100, v101, s[2:3]
	v_mul_f32_e32 v100, 0x37800000, v99
	v_cndmask_b32_e32 v99, v99, v100, vcc
	v_cmp_class_f32_e32 vcc, v98, v207
	s_nop 1
	v_cndmask_b32_e32 v98, v99, v98, vcc
	v_div_scale_f32 v99, s[2:3], v98, v98, 1.0
	v_rcp_f32_e32 v100, v99
	s_cselect_b64 s[2:3], -1, 0
	s_lshr_b32 s14, 0x100c, s46
	s_bitcmp1_b32 s14, 0
	v_fma_f32 v101, -v99, v100, 1.0
	v_fmac_f32_e32 v100, v101, v100
	v_div_scale_f32 v101, vcc, 1.0, v98, 1.0
	v_mul_f32_e32 v102, v101, v100
	v_fma_f32 v103, -v99, v102, v101
	v_fmac_f32_e32 v102, v103, v100
	s_cselect_b64 s[14:15], -1, 0
	v_fma_f32 v99, -v99, v102, v101
	s_and_b64 s[2:3], s[2:3], s[14:15]
	v_div_fmas_f32 v99, v99, v100, v102
	s_cmp_eq_u32 s46, 12
	v_and_or_b32 v100, v208, 64, v184
	v_and_b32_e32 v101, 64, v208
	s_cselect_b64 s[24:25], -1, 0
	s_mov_b64 s[46:47], -1
	s_and_b64 vcc, exec, s[2:3]
	v_add_u32_e32 v181, 64, v101
	v_lshlrev_b32_e32 v211, 2, v100
	s_cbranch_vccnz .LBB0_542
	v_add_u32_e32 v214, 64, v101
	v_lshlrev_b32_e32 v219, 2, v100
	s_mov_b64 s[46:47], 0

; __device__ __forceinline__ float row_rstd(const float* ss, int row) { return 1.0f / sqrtf(ss[row] * (1.0f / DM) + 1e-6f); }
;     __device__ __forceinline__ void operator()(const f32x4 (&acc)[2][2][4][2], const Unit& u, int wr, int wc, int fr, int fq) const {
;         const int row0 = u.pm * BM + wr * 64 + fr, col0 = u.pn * BM + wc * 64 + 8 * fq;
;         const bool lat = u.pm < ML / BM; const int s = lat ? (u.pm >> 5) : 4;
;         const float* bp = bias + (size_t)s * BIAS_N + col0;
;         const f32x4 b00 = *(const f32x4*)bp, b01 = *(const f32x4*)(bp + 4), b10 = *(const f32x4*)(bp + 32), b11 = *(const f32x4*)(bp + 36);
;         const int lane = fq * 16 + fr;
;         const float rsl0 = row_rstd(ss, u.pm * BM + wr * 64 + lane), rsl1 = row_rstd(ss, u.pm * BM + HALF + wr * 64 + lane);
;         const bool odd = (fr & 1) != 0;
;         const bool ktile = (u.pn == 2) || (u.pn == 3) || (u.pn == 12), wa = (u.pn == 12);
;         float part[2][4]; f32x4 g00, g01, g10, g11;
.LBB0_2148:
	s_lshl_b32 s11, s2, 8
	s_add_i32 s11, s11, s50
	s_lshl_b64 s[2:3], s[22:23], 2
	v_lshl_or_b32 v182, s18, 8, v201
	s_add_u32 s2, s51, s2
	v_or_b32_e32 v98, s11, v186
	s_addc_u32 s3, s52, s3
	v_ashrrev_i32_e32 v183, 31, v182
	v_ashrrev_i32_e32 v99, 31, v98
	v_lshl_add_u64 v[38:39], v[182:183], 2, s[2:3]
	v_lshl_add_u64 v[98:99], v[98:99], 2, s[6:7]
	global_load_dwordx4 v[42:45], v[38:39], off offset:16
	global_load_dwordx4 v[46:49], v[38:39], off
	global_load_dwordx4 v[34:37], v[38:39], off offset:144
	s_nop 0
	global_load_dwordx4 v[38:41], v[38:39], off offset:128
	s_cmp_lt_u32 s18, 13
	global_load_dword v98, v[98:99], off
	v_add_u32_e32 v110, s11, v192
	v_ashrrev_i32_e32 v111, 31, v110
	v_lshl_add_u64 v[110:111], v[110:111], 2, s[6:7]
	global_load_dword v112, v[110:111], off
	s_waitcnt vmcnt(0)
	v_fmamk_f32 v98, v98, 0x3a000000, v205
	v_cmp_gt_f32_e32 vcc, s58, v98
	v_mul_f32_e32 v99, 0x4f800000, v98
	s_nop 0
	v_cndmask_b32_e32 v98, v98, v99, vcc
	v_sqrt_f32_e32 v99, v98
	s_nop 0
	v_add_u32_e32 v100, -1, v99
	v_fma_f32 v101, -v100, v99, v98
	v_cmp_ge_f32_e64 s[2:3], 0, v101
	v_add_u32_e32 v101, 1, v99
	s_nop 0
	v_cndmask_b32_e64 v100, v99, v100, s[2:3]
	v_fma_f32 v99, -v101, v99, v98
	v_cmp_lt_f32_e64 s[2:3], 0, v99
	s_nop 1
	v_cndmask_b32_e64 v99, v100, v101, s[2:3]
	v_mul_f32_e32 v100, 0x37800000, v99
	v_cndmask_b32_e32 v99, v99, v100, vcc
	v_cmp_class_f32_e32 vcc, v98, v206
	s_nop 1
	v_cndmask_b32_e32 v98, v99, v98, vcc
	v_div_scale_f32 v99, s[2:3], v98, v98, 1.0
	v_rcp_f32_e32 v100, v99
	s_nop 0
	v_fma_f32 v101, -v99, v100, 1.0
	v_fmac_f32_e32 v100, v101, v100
	v_div_scale_f32 v101, vcc, 1.0, v98, 1.0
	v_mul_f32_e32 v102, v101, v100
	v_fma_f32 v103, -v99, v102, v101
	v_fmac_f32_e32 v102, v103, v100
	v_fma_f32 v99, -v99, v102, v101
	v_div_fmas_f32 v99, v99, v100, v102
	v_div_fixup_f32 v215, v99, v98, 1.0
	v_fmamk_f32 v98, v112, 0x3a000000, v205
	v_cmp_gt_f32_e32 vcc, s58, v98
	v_mul_f32_e32 v99, 0x4f800000, v98
	s_nop 0
	v_cndmask_b32_e32 v98, v98, v99, vcc
	v_sqrt_f32_e32 v99, v98
	s_nop 0
	v_add_u32_e32 v100, -1, v99
	v_fma_f32 v101, -v100, v99, v98
	v_cmp_ge_f32_e64 s[2:3], 0, v101
	v_add_u32_e32 v101, 1, v99
	s_nop 0
	v_cndmask_b32_e64 v100, v99, v100, s[2:3]
	v_fma_f32 v99, -v101, v99, v98
	v_cmp_lt_f32_e64 s[2:3], 0, v99
	s_nop 1
	v_cndmask_b32_e64 v99, v100, v101, s[2:3]
	v_mul_f32_e32 v100, 0x37800000, v99
	v_cndmask_b32_e32 v99, v99, v100, vcc
	v_cmp_class_f32_e32 vcc, v98, v206
	s_nop 1
	v_cndmask_b32_e32 v98, v99, v98, vcc
	v_div_scale_f32 v99, s[2:3], v98, v98, 1.0
	v_rcp_f32_e32 v100, v99
	s_cselect_b64 s[2:3], -1, 0
	s_lshr_b32 s13, 0x100c, s18
	s_bitcmp1_b32 s13, 0
	v_fma_f32 v101, -v99, v100, 1.0
	v_fmac_f32_e32 v100, v101, v100
	v_div_scale_f32 v101, vcc, 1.0, v98, 1.0
	v_mul_f32_e32 v102, v101, v100
	v_fma_f32 v103, -v99, v102, v101
	v_fmac_f32_e32 v102, v103, v100
	s_cselect_b64 s[22:23], -1, 0
	v_fma_f32 v99, -v99, v102, v101
	s_and_b64 s[2:3], s[2:3], s[22:23]
	v_div_fmas_f32 v99, v99, v100, v102
	s_cmp_eq_u32 s18, 12
	v_and_or_b32 v100, v207, 64, v1
	v_and_b32_e32 v101, 64, v207
	s_cselect_b64 s[18:19], -1, 0
	s_mov_b64 s[22:23], -1
	s_and_b64 vcc, exec, s[2:3]
	v_add_u32_e32 v181, 64, v101
	v_lshlrev_b32_e32 v210, 2, v100
	s_cbranch_vccnz .LBB0_2150
	v_add_u32_e32 v213, 64, v101
	v_lshlrev_b32_e32 v218, 2, v100
	s_mov_b64 s[22:23], 0
